# v030 plus non-temporal hint on the PN input-row loads (read once per layer)
# speedup vs baseline: 1.0026x; 1.0026x over previous
; DI void phase_norm(const Params& p, int l, const float* xin, LAS unsigned char* lds, int G, int bid) {
;     ...
;     for (int i = tid; i < 4096; i += NT) { const int b_ = i >> 10, k_ = i & 1023; pa[i] = ng[k_] * (1.0f + ada[b_ * 3072 + 1024 + k_]); pb[i] = ada[b_ * 3072 + k_]; }
;     __syncthreads();
;     f32x4 w0[4][4], w1[4][4];
; #pragma unroll
;     for (int j = 0; j < 4; ++j)
; #pragma unroll
;         for (int e = 0; e < 4; ++e) { const int k = 256 * j + 4 * lane + e; w0[j][e] = *(const f32x4*)(wg + (size_t)k * 8); w1[j][e] = *(const f32x4*)(wg + (size_t)k * 8 + 4); }
;     f32x4 vn[4];
;     if (gw < M) {
; #pragma unroll
;         for (int j = 0; j < 4; ++j) vn[j] = ((const f32x4*)(xin + (size_t)gw * D) + lane)[64 * j]; }
.LBB0_137:
	s_or_b64 exec, exec, s[18:19]
	v_ashrrev_i32_e32 v42, 6, v2
	v_readlane_b32 s0, v250, 2
	s_lshl_b64 s[18:19], s[26:27], 15
	v_readlane_b32 s1, v250, 3
	v_add_u32_e32 v178, s0, v42
	s_mov_b32 s0, 0x8000
	v_cmp_gt_i32_e32 vcc, s0, v178
	s_waitcnt lgkmcnt(0)
	s_barrier
	s_and_saveexec_b64 s[46:47], vcc
	s_cbranch_execz .LBB0_144
	v_readlane_b32 s0, v252, 14
	s_add_u32 s0, s0, s18
	v_readlane_b32 s1, v252, 15
	v_and_b32_e32 v43, 63, v2
	s_addc_u32 s1, s1, s19
	v_lshlrev_b32_e32 v0, 7, v43
	v_lshl_add_u64 v[44:45], s[0:1], 0, v[0:1]
	v_add_co_u32_e32 v34, vcc, s89, v44
	s_movk_i32 s6, 0x4000
	s_nop 0
	v_addc_co_u32_e32 v35, vcc, 0, v45, vcc
	s_mov_b64 s[8:9], 0x2040
	v_add_co_u32_e32 v50, vcc, s6, v44
	v_lshl_add_u64 v[46:47], v[44:45], 0, s[8:9]
	s_mov_b64 s[8:9], 0x4040
	v_addc_co_u32_e32 v51, vcc, 0, v45, vcc
	s_movk_i32 s6, 0x6000
	v_lshl_add_u64 v[62:63], v[44:45], 0, s[8:9]
	s_mov_b64 s[8:9], 0x6040
	v_add_co_u32_e32 v66, vcc, s6, v44
	v_ashrrev_i32_e32 v179, 31, v178
	v_lshl_add_u64 v[78:79], v[44:45], 0, s[8:9]
	v_addc_co_u32_e32 v67, vcc, 0, v45, vcc
	v_lshlrev_b64 v[44:45], 12, v[178:179]
	global_load_dwordx4 v[2:5], v0, s[0:1] offset:48
	global_load_dwordx4 v[6:9], v0, s[0:1] offset:32
	global_load_dwordx4 v[10:13], v0, s[0:1] offset:16
	global_load_dwordx4 v[14:17], v0, s[0:1]
	global_load_dwordx4 v[18:21], v0, s[0:1] offset:112
	global_load_dwordx4 v[22:25], v0, s[0:1] offset:96
	global_load_dwordx4 v[26:29], v0, s[0:1] offset:80
	global_load_dwordx4 v[30:33], v0, s[0:1] offset:64
	v_or_b32_e32 v94, 0x2000, v0
	v_or_b32_e32 v110, 0x4000, v0
	v_or_b32_e32 v126, 0x6000, v0
	v_lshl_add_u64 v[44:45], s[4:5], 0, v[44:45]
	v_lshlrev_b32_e32 v0, 4, v43
	v_lshl_add_u64 v[82:83], v[44:45], 0, v[0:1]
	v_and_b32_e32 v44, 64, v203
	v_add_u32_e32 v44, 64, v44
	v_xor_b32_e32 v45, 1, v203
	v_cmp_lt_i32_e32 vcc, v45, v44
	v_readlane_b32 s6, v250, 4
	v_lshlrev_b64 v[172:173], 11, v[178:179]
	v_cndmask_b32_e32 v45, v203, v45, vcc
	v_lshlrev_b32_e32 v163, 2, v45
	v_xor_b32_e32 v45, 2, v203
	v_cmp_lt_i32_e32 vcc, v45, v44
	v_add_u32_e32 v42, s6, v42
	v_and_b32_e32 v220, 15, v43
	v_lshrrev_b32_e32 v221, 1, v43
	v_and_b32_e32 v221, 24, v221
	v_or_b32_e32 v221, 0x200000, v221
	v_cmp_eq_u32_e64 s[40:41], 0, v220
	v_cndmask_b32_e32 v45, v203, v45, vcc
	v_lshlrev_b32_e32 v180, 2, v45
	v_xor_b32_e32 v45, 4, v203
	v_cmp_lt_i32_e32 vcc, v45, v44
	v_lshl_or_b32 v172, v43, 3, v172
	v_ashrrev_i32_e32 v43, 31, v42
	v_cndmask_b32_e32 v45, v203, v45, vcc
	v_lshlrev_b32_e32 v181, 2, v45
	v_xor_b32_e32 v45, 8, v203
	v_cmp_lt_i32_e32 vcc, v45, v44
	v_lshlrev_b64 v[42:43], 12, v[42:43]
	v_or_b32_e32 v42, v42, v0
	v_cndmask_b32_e32 v45, v203, v45, vcc
	v_lshlrev_b32_e32 v182, 2, v45
	v_xor_b32_e32 v45, 16, v203
	v_cmp_lt_i32_e32 vcc, v45, v44
	global_load_dwordx4 v[34:37], v[34:35], off offset:64
	s_nop 0
	global_load_dwordx4 v[38:41], v[46:47], off offset:48
	v_cndmask_b32_e32 v45, v203, v45, vcc
	v_lshlrev_b32_e32 v183, 2, v45
	v_xor_b32_e32 v45, 32, v203
	v_cmp_lt_i32_e32 vcc, v45, v44
	v_lshl_add_u64 v[174:175], s[4:5], 0, v[42:43]
	v_add_u32_e32 v185, 0, v0
	v_cndmask_b32_e32 v44, v203, v45, vcc
	v_lshlrev_b32_e32 v184, 2, v44
	global_load_dwordx4 v[42:45], v[46:47], off offset:32
	s_nop 0
	global_load_dwordx4 v[46:49], v[46:47], off offset:16
	s_nop 0
	global_load_dwordx4 v[50:53], v[50:51], off offset:64
	s_nop 0
	global_load_dwordx4 v[54:57], v[62:63], off offset:48
	global_load_dwordx4 v[58:61], v[62:63], off offset:32
	s_nop 0
	global_load_dwordx4 v[62:65], v[62:63], off offset:16
	s_nop 0
	global_load_dwordx4 v[66:69], v[66:67], off offset:64
	s_nop 0
	global_load_dwordx4 v[70:73], v[78:79], off offset:48
	global_load_dwordx4 v[74:77], v[78:79], off offset:32
	s_nop 0
	global_load_dwordx4 v[78:81], v[78:79], off offset:16
	s_nop 0
	global_load_dwordx4 v[158:161], v[82:83], off nt
	global_load_dwordx4 v[154:157], v[82:83], off offset:1024 nt
	global_load_dwordx4 v[150:153], v[82:83], off offset:2048 nt
	global_load_dwordx4 v[146:149], v[82:83], off offset:3072 nt
	s_nop 0
	global_load_dwordx4 v[82:85], v94, s[0:1] offset:48
	global_load_dwordx4 v[86:89], v94, s[0:1] offset:32
	global_load_dwordx4 v[90:93], v94, s[0:1] offset:16
	s_nop 0
	global_load_dwordx4 v[94:97], v94, s[0:1]
	s_nop 0
	global_load_dwordx4 v[98:101], v110, s[0:1] offset:48
	global_load_dwordx4 v[102:105], v110, s[0:1] offset:32
	global_load_dwordx4 v[106:109], v110, s[0:1] offset:16
	s_nop 0
	global_load_dwordx4 v[110:113], v110, s[0:1]
	s_nop 0
	global_load_dwordx4 v[114:117], v126, s[0:1] offset:48
	global_load_dwordx4 v[118:121], v126, s[0:1] offset:32
	global_load_dwordx4 v[122:125], v126, s[0:1] offset:16
	s_nop 0
	global_load_dwordx4 v[126:129], v126, s[0:1]
	s_mov_b64 s[48:49], 0
	v_lshlrev_b64 v[176:177], 5, v[178:179]
	v_readlane_b32 s98, v250, 15
	v_readlane_b32 s99, v250, 16
	v_readlane_b32 s100, v250, 17
	v_readlane_b32 s101, v250, 18
	v_readlane_b32 s8, v250, 19
	v_readlane_b32 s9, v250, 20
	s_branch .LBB0_140

; DI void phase_norm(const Params& p, int l, const float* xin, LAS unsigned char* lds, int G, int bid) {
;     ...
;     for (int row = gw; row < M; row += NGW) {
;         const int b = row / S;
;         f32x4 v[4]; float ss = 0.f;
; #pragma unroll
;         for (int j = 0; j < 4; ++j) v[j] = vn[j];
;         if (row + NGW < M) {
.LBB0_140:
	v_add_u32_e32 v179, s10, v178
	s_mov_b32 s0, 0x8000
	v_cmp_gt_i32_e32 vcc, s0, v179
	s_movk_i32 s0, 0x7fff
	v_cmp_lt_i32_e64 s[42:43], s0, v179


; DI void phase_norm(const Params& p, int l, const float* xin, LAS unsigned char* lds, int G, int bid) {
;     ...
;         if (row + NGW < M) {
; #pragma unroll
;             for (int j = 0; j < 4; ++j) vn[j] = ((const f32x4*)(xin + (size_t)(row + NGW) * D) + lane)[64 * j]; }
	s_waitcnt vmcnt(12)
	s_and_saveexec_b64 s[0:1], vcc
	s_cbranch_execz .LBB0_142
	global_load_dwordx4 v[130:133], v[174:175], off nt
	global_load_dwordx4 v[134:137], v[174:175], off offset:1024 nt
	global_load_dwordx4 v[138:141], v[174:175], off offset:2048 nt
	global_load_dwordx4 v[142:145], v[174:175], off offset:3072 nt
